# s_setprio flips also removed from the two short (K=256) GEMM loops (kv up-projection, pool maps)
# speedup vs baseline: 1.0103x; 1.0103x over previous
.LBB0_1681:
	s_add_u32 s31, s12, s42
	s_addc_u32 s33, s13, s43
	s_add_u32 s35, s31, 0x100
	s_addc_u32 s46, s33, 0
	s_and_b64 s[44:45], s[40:41], exec
	s_cselect_b32 s47, s0, s46
	s_cselect_b32 s46, s1, s35
	s_add_u32 s35, s10, s42
	s_addc_u32 s42, s11, s43
	s_add_u32 s35, s35, 0x100
	s_addc_u32 s42, s42, 0
	s_add_i32 s72, 0, 0x10000
	s_and_b64 s[40:41], s[40:41], exec
	s_cselect_b32 s49, s7, s42
	s_cselect_b32 s48, s9, s35
	s_add_u32 s50, s31, 0x10080
	s_addc_u32 s51, s33, 0
	s_add_i32 s82, s72, s58
	s_add_i32 m0, s59, 0xc000
	s_add_i32 s83, s59, 0xe000
	s_add_i32 s75, 0, 0x14000
	s_add_i32 s74, s82, 0x2000
	s_add_u32 s44, s48, 0x10000
	v_add_u32_e32 v148, s72, v150
	s_addc_u32 s45, s49, 0
	s_add_i32 s69, s75, s58
	ds_read_b128 v[136:139], v148
	ds_read_b128 v[140:143], v148 offset:1024
	ds_read_b128 v[144:147], v148 offset:2048
	ds_read_b128 v[152:155], v148 offset:3072
	s_add_i32 s68, s69, 0x2000
	s_add_i32 s67, 0, 0x18000
	s_add_u32 s42, s46, 0x10000
	s_addc_u32 s43, s47, 0
	s_add_i32 s35, s67, s58
	s_add_i32 s33, 0, 0x1c000
	s_add_i32 s31, s35, 0x2000
	s_add_u32 s40, s48, 0x10080
	s_addc_u32 s41, s49, 0
	s_add_i32 s73, s33, s58
	s_add_i32 s72, s73, 0x2000
	v_lshl_add_u64 v[148:149], s[50:51], 0, v[128:129]
	ds_read_b128 v[156:159], v151
	ds_read_b128 v[160:163], v151 offset:1024
	ds_read_b128 v[164:167], v151 offset:2048
	ds_read_b128 v[168:171], v151 offset:3072
	ds_read_b128 v[172:175], v151 offset:4096
	ds_read_b128 v[176:179], v151 offset:5120
	ds_read_b128 v[180:183], v151 offset:6144
	ds_read_b128 v[184:187], v151 offset:7168
	global_load_lds_dwordx4 v[148:149], off
	v_lshl_add_u64 v[148:149], s[50:51], 0, v[132:133]
	s_mov_b32 m0, s83
	s_nop 0
	global_load_lds_dwordx4 v[148:149], off
	s_waitcnt lgkmcnt(8)
	s_barrier
	s_waitcnt lgkmcnt(0)
	v_mfma_f32_16x16x32_bf16 v[124:127], v[136:139], v[156:159], v[124:127]
	v_mfma_f32_16x16x32_bf16 v[120:123], v[144:147], v[156:159], v[120:123]
	v_mfma_f32_16x16x32_bf16 v[108:111], v[136:139], v[164:167], v[108:111]
	v_mfma_f32_16x16x32_bf16 v[104:107], v[144:147], v[164:167], v[104:107]
	v_mfma_f32_16x16x32_bf16 v[92:95], v[136:139], v[172:175], v[92:95]
	v_mfma_f32_16x16x32_bf16 v[88:91], v[144:147], v[172:175], v[88:91]
	v_mfma_f32_16x16x32_bf16 v[76:79], v[136:139], v[180:183], v[76:79]
	v_mfma_f32_16x16x32_bf16 v[72:75], v[144:147], v[180:183], v[72:75]
	v_mfma_f32_16x16x32_bf16 v[124:127], v[140:143], v[160:163], v[124:127]
	v_mfma_f32_16x16x32_bf16 v[120:123], v[152:155], v[160:163], v[120:123]
	v_mfma_f32_16x16x32_bf16 v[108:111], v[140:143], v[168:171], v[108:111]
	v_mfma_f32_16x16x32_bf16 v[104:107], v[152:155], v[168:171], v[104:107]
	v_mfma_f32_16x16x32_bf16 v[92:95], v[140:143], v[176:179], v[92:95]
	v_mfma_f32_16x16x32_bf16 v[88:91], v[152:155], v[176:179], v[88:91]
	v_mfma_f32_16x16x32_bf16 v[76:79], v[140:143], v[184:187], v[76:79]
	v_mfma_f32_16x16x32_bf16 v[72:75], v[152:155], v[184:187], v[72:75]
	s_barrier
	v_add_u32_e32 v148, s75, v150
	s_mov_b32 m0, s82
	ds_read_b128 v[188:191], v148
	ds_read_b128 v[198:201], v148 offset:1024
	ds_read_b128 v[206:209], v148 offset:2048
	ds_read_b128 v[210:213], v148 offset:3072
	v_lshl_add_u64 v[148:149], s[48:49], 0, v[130:131]
	global_load_lds_dwordx4 v[148:149], off
	v_lshl_add_u64 v[214:215], s[48:49], 0, v[134:135]
	s_mov_b32 m0, s74
	s_nop 0
	global_load_lds_dwordx4 v[214:215], off
	s_barrier
	s_waitcnt lgkmcnt(0)
	v_mfma_f32_16x16x32_bf16 v[116:119], v[188:191], v[156:159], v[116:119]
	v_mfma_f32_16x16x32_bf16 v[112:115], v[206:209], v[156:159], v[112:115]
	v_mfma_f32_16x16x32_bf16 v[100:103], v[188:191], v[164:167], v[100:103]
	v_mfma_f32_16x16x32_bf16 v[96:99], v[206:209], v[164:167], v[96:99]
	v_mfma_f32_16x16x32_bf16 v[84:87], v[188:191], v[172:175], v[84:87]
	v_mfma_f32_16x16x32_bf16 v[80:83], v[206:209], v[172:175], v[80:83]
	v_mfma_f32_16x16x32_bf16 v[68:71], v[188:191], v[180:183], v[68:71]
	v_mfma_f32_16x16x32_bf16 v[64:67], v[206:209], v[180:183], v[64:67]
	v_mfma_f32_16x16x32_bf16 v[116:119], v[198:201], v[160:163], v[116:119]
	v_mfma_f32_16x16x32_bf16 v[112:115], v[210:213], v[160:163], v[112:115]
	v_mfma_f32_16x16x32_bf16 v[100:103], v[198:201], v[168:171], v[100:103]
	v_mfma_f32_16x16x32_bf16 v[96:99], v[210:213], v[168:171], v[96:99]
	v_mfma_f32_16x16x32_bf16 v[84:87], v[198:201], v[176:179], v[84:87]
	v_mfma_f32_16x16x32_bf16 v[80:83], v[210:213], v[176:179], v[80:83]
	v_mfma_f32_16x16x32_bf16 v[68:71], v[198:201], v[184:187], v[68:71]
	v_mfma_f32_16x16x32_bf16 v[64:67], v[210:213], v[184:187], v[64:67]
	s_mov_b32 m0, s59
	v_lshl_add_u64 v[216:217], s[46:47], 0, v[128:129]
	s_barrier
	ds_read_b128 v[156:159], v151 offset:16384
	ds_read_b128 v[160:163], v151 offset:17408
	ds_read_b128 v[164:167], v151 offset:18432
	ds_read_b128 v[168:171], v151 offset:19456
	ds_read_b128 v[172:175], v151 offset:20480
	ds_read_b128 v[176:179], v151 offset:21504
	ds_read_b128 v[180:183], v151 offset:22528
	ds_read_b128 v[184:187], v151 offset:23552
	global_load_lds_dwordx4 v[216:217], off
	v_lshl_add_u64 v[218:219], s[46:47], 0, v[132:133]
	s_mov_b32 m0, s60
	s_nop 0
	global_load_lds_dwordx4 v[218:219], off
	s_barrier
	s_waitcnt lgkmcnt(0)
	v_mfma_f32_16x16x32_bf16 v[60:63], v[136:139], v[156:159], v[60:63]
	v_mfma_f32_16x16x32_bf16 v[56:59], v[144:147], v[156:159], v[56:59]
	v_mfma_f32_16x16x32_bf16 v[44:47], v[136:139], v[164:167], v[44:47]
	v_mfma_f32_16x16x32_bf16 v[40:43], v[144:147], v[164:167], v[40:43]
	v_mfma_f32_16x16x32_bf16 v[28:31], v[136:139], v[172:175], v[28:31]
	v_mfma_f32_16x16x32_bf16 v[24:27], v[144:147], v[172:175], v[24:27]
	v_mfma_f32_16x16x32_bf16 v[12:15], v[136:139], v[180:183], v[12:15]
	v_mfma_f32_16x16x32_bf16 v[8:11], v[144:147], v[180:183], v[8:11]
	v_mfma_f32_16x16x32_bf16 v[60:63], v[140:143], v[160:163], v[60:63]
	v_mfma_f32_16x16x32_bf16 v[56:59], v[152:155], v[160:163], v[56:59]
	v_mfma_f32_16x16x32_bf16 v[44:47], v[140:143], v[168:171], v[44:47]
	v_mfma_f32_16x16x32_bf16 v[40:43], v[152:155], v[168:171], v[40:43]
	v_mfma_f32_16x16x32_bf16 v[28:31], v[140:143], v[176:179], v[28:31]
	v_mfma_f32_16x16x32_bf16 v[24:27], v[152:155], v[176:179], v[24:27]
	v_mfma_f32_16x16x32_bf16 v[12:15], v[140:143], v[184:187], v[12:15]
	v_mfma_f32_16x16x32_bf16 v[8:11], v[152:155], v[184:187], v[8:11]
	s_barrier
	s_mov_b32 m0, s69
	v_lshl_add_u64 v[136:137], s[44:45], 0, v[130:131]
	global_load_lds_dwordx4 v[136:137], off
	v_lshl_add_u64 v[136:137], s[44:45], 0, v[134:135]
	s_mov_b32 m0, s68
	s_nop 0
	global_load_lds_dwordx4 v[136:137], off
	s_waitcnt vmcnt(6)
	s_barrier
	v_mfma_f32_16x16x32_bf16 v[52:55], v[188:191], v[156:159], v[52:55]
	v_mfma_f32_16x16x32_bf16 v[48:51], v[206:209], v[156:159], v[48:51]
	v_mfma_f32_16x16x32_bf16 v[36:39], v[188:191], v[164:167], v[36:39]
	v_mfma_f32_16x16x32_bf16 v[32:35], v[206:209], v[164:167], v[32:35]
	v_mfma_f32_16x16x32_bf16 v[20:23], v[188:191], v[172:175], v[20:23]
	v_mfma_f32_16x16x32_bf16 v[16:19], v[206:209], v[172:175], v[16:19]
	v_mfma_f32_16x16x32_bf16 v[4:7], v[188:191], v[180:183], v[4:7]
	v_mfma_f32_16x16x32_bf16 v[0:3], v[206:209], v[180:183], v[0:3]
	v_mfma_f32_16x16x32_bf16 v[52:55], v[198:201], v[160:163], v[52:55]
	v_mfma_f32_16x16x32_bf16 v[48:51], v[210:213], v[160:163], v[48:51]
	v_mfma_f32_16x16x32_bf16 v[36:39], v[198:201], v[168:171], v[36:39]
	v_mfma_f32_16x16x32_bf16 v[32:35], v[210:213], v[168:171], v[32:35]
	v_mfma_f32_16x16x32_bf16 v[20:23], v[198:201], v[176:179], v[20:23]
	v_mfma_f32_16x16x32_bf16 v[16:19], v[210:213], v[176:179], v[16:19]
	v_mfma_f32_16x16x32_bf16 v[4:7], v[198:201], v[184:187], v[4:7]
	v_mfma_f32_16x16x32_bf16 v[0:3], v[210:213], v[184:187], v[0:3]
	v_add_u32_e32 v152, s67, v150
	s_barrier
	ds_read_b128 v[136:139], v152
	ds_read_b128 v[140:143], v152 offset:1024
	ds_read_b128 v[144:147], v152 offset:2048
	ds_read_b128 v[152:155], v152 offset:3072
	s_mov_b32 m0, s61
	v_lshl_add_u64 v[188:189], s[42:43], 0, v[128:129]
	ds_read_b128 v[156:159], v151 offset:32768
	ds_read_b128 v[160:163], v151 offset:33792
	ds_read_b128 v[164:167], v151 offset:34816
	ds_read_b128 v[168:171], v151 offset:35840
	ds_read_b128 v[172:175], v151 offset:36864
	ds_read_b128 v[176:179], v151 offset:37888
	ds_read_b128 v[180:183], v151 offset:38912
	ds_read_b128 v[184:187], v151 offset:39936
	global_load_lds_dwordx4 v[188:189], off
	v_lshl_add_u64 v[188:189], s[42:43], 0, v[132:133]
	s_mov_b32 m0, s62
	s_nop 0
	global_load_lds_dwordx4 v[188:189], off
	s_waitcnt lgkmcnt(8)
	s_barrier
	s_waitcnt lgkmcnt(0)
	v_mfma_f32_16x16x32_bf16 v[124:127], v[136:139], v[156:159], v[124:127]
	v_mfma_f32_16x16x32_bf16 v[120:123], v[144:147], v[156:159], v[120:123]
	v_mfma_f32_16x16x32_bf16 v[108:111], v[136:139], v[164:167], v[108:111]
	v_mfma_f32_16x16x32_bf16 v[104:107], v[144:147], v[164:167], v[104:107]
	v_mfma_f32_16x16x32_bf16 v[92:95], v[136:139], v[172:175], v[92:95]
	v_mfma_f32_16x16x32_bf16 v[88:91], v[144:147], v[172:175], v[88:91]
	v_mfma_f32_16x16x32_bf16 v[76:79], v[136:139], v[180:183], v[76:79]
	v_mfma_f32_16x16x32_bf16 v[72:75], v[144:147], v[180:183], v[72:75]
	v_mfma_f32_16x16x32_bf16 v[124:127], v[140:143], v[160:163], v[124:127]
	v_mfma_f32_16x16x32_bf16 v[120:123], v[152:155], v[160:163], v[120:123]
	v_mfma_f32_16x16x32_bf16 v[108:111], v[140:143], v[168:171], v[108:111]
	v_mfma_f32_16x16x32_bf16 v[104:107], v[152:155], v[168:171], v[104:107]
	v_mfma_f32_16x16x32_bf16 v[92:95], v[140:143], v[176:179], v[92:95]
	v_mfma_f32_16x16x32_bf16 v[88:91], v[152:155], v[176:179], v[88:91]
	v_mfma_f32_16x16x32_bf16 v[76:79], v[140:143], v[184:187], v[76:79]
	v_mfma_f32_16x16x32_bf16 v[72:75], v[152:155], v[184:187], v[72:75]
	s_barrier
	s_mov_b32 m0, s35
	v_add_u32_e32 v192, s33, v150
	v_lshl_add_u64 v[148:149], v[148:149], 0, s[80:81]
	ds_read_b128 v[188:191], v192
	ds_read_b128 v[198:201], v192 offset:1024
	ds_read_b128 v[206:209], v192 offset:2048
	ds_read_b128 v[210:213], v192 offset:3072
	global_load_lds_dwordx4 v[148:149], off
	v_lshl_add_u64 v[148:149], v[214:215], 0, s[80:81]
	s_mov_b32 m0, s31
	s_nop 0
	global_load_lds_dwordx4 v[148:149], off
	s_barrier
	s_waitcnt lgkmcnt(0)
	v_mfma_f32_16x16x32_bf16 v[116:119], v[188:191], v[156:159], v[116:119]
	v_mfma_f32_16x16x32_bf16 v[112:115], v[206:209], v[156:159], v[112:115]
	v_mfma_f32_16x16x32_bf16 v[100:103], v[188:191], v[164:167], v[100:103]
	v_mfma_f32_16x16x32_bf16 v[96:99], v[206:209], v[164:167], v[96:99]
	v_mfma_f32_16x16x32_bf16 v[84:87], v[188:191], v[172:175], v[84:87]
	v_mfma_f32_16x16x32_bf16 v[80:83], v[206:209], v[172:175], v[80:83]
	v_mfma_f32_16x16x32_bf16 v[68:71], v[188:191], v[180:183], v[68:71]
	v_mfma_f32_16x16x32_bf16 v[64:67], v[206:209], v[180:183], v[64:67]
	v_mfma_f32_16x16x32_bf16 v[116:119], v[198:201], v[160:163], v[116:119]
	v_mfma_f32_16x16x32_bf16 v[112:115], v[210:213], v[160:163], v[112:115]
	v_mfma_f32_16x16x32_bf16 v[100:103], v[198:201], v[168:171], v[100:103]
	v_mfma_f32_16x16x32_bf16 v[96:99], v[210:213], v[168:171], v[96:99]
	v_mfma_f32_16x16x32_bf16 v[84:87], v[198:201], v[176:179], v[84:87]
	v_mfma_f32_16x16x32_bf16 v[80:83], v[210:213], v[176:179], v[80:83]
	v_mfma_f32_16x16x32_bf16 v[68:71], v[198:201], v[184:187], v[68:71]
	v_mfma_f32_16x16x32_bf16 v[64:67], v[210:213], v[184:187], v[64:67]
	s_mov_b32 m0, s63
	v_lshl_add_u64 v[148:149], v[216:217], 0, s[80:81]
	s_barrier
	ds_read_b128 v[156:159], v151 offset:49152
	ds_read_b128 v[160:163], v151 offset:50176
	ds_read_b128 v[164:167], v151 offset:51200
	ds_read_b128 v[168:171], v151 offset:52224
	ds_read_b128 v[172:175], v151 offset:53248
	ds_read_b128 v[176:179], v151 offset:54272
	ds_read_b128 v[180:183], v151 offset:55296
	ds_read_b128 v[184:187], v151 offset:56320
	global_load_lds_dwordx4 v[148:149], off
	v_lshl_add_u64 v[148:149], v[218:219], 0, s[80:81]
	s_mov_b32 m0, s64
	s_nop 0
	global_load_lds_dwordx4 v[148:149], off
	s_barrier
	s_waitcnt lgkmcnt(0)
	v_mfma_f32_16x16x32_bf16 v[60:63], v[136:139], v[156:159], v[60:63]
	v_mfma_f32_16x16x32_bf16 v[56:59], v[144:147], v[156:159], v[56:59]
	v_mfma_f32_16x16x32_bf16 v[44:47], v[136:139], v[164:167], v[44:47]
	v_mfma_f32_16x16x32_bf16 v[40:43], v[144:147], v[164:167], v[40:43]
	v_mfma_f32_16x16x32_bf16 v[28:31], v[136:139], v[172:175], v[28:31]
	v_mfma_f32_16x16x32_bf16 v[24:27], v[144:147], v[172:175], v[24:27]
	v_mfma_f32_16x16x32_bf16 v[12:15], v[136:139], v[180:183], v[12:15]
	v_mfma_f32_16x16x32_bf16 v[8:11], v[144:147], v[180:183], v[8:11]
	v_mfma_f32_16x16x32_bf16 v[60:63], v[140:143], v[160:163], v[60:63]
	v_mfma_f32_16x16x32_bf16 v[56:59], v[152:155], v[160:163], v[56:59]
	v_mfma_f32_16x16x32_bf16 v[44:47], v[140:143], v[168:171], v[44:47]
	v_mfma_f32_16x16x32_bf16 v[40:43], v[152:155], v[168:171], v[40:43]
	v_mfma_f32_16x16x32_bf16 v[28:31], v[140:143], v[176:179], v[28:31]
	v_mfma_f32_16x16x32_bf16 v[24:27], v[152:155], v[176:179], v[24:27]
	v_mfma_f32_16x16x32_bf16 v[12:15], v[140:143], v[184:187], v[12:15]
	v_mfma_f32_16x16x32_bf16 v[8:11], v[152:155], v[184:187], v[8:11]
	s_barrier
	s_mov_b32 m0, s73
	v_lshl_add_u64 v[136:137], s[40:41], 0, v[130:131]
	global_load_lds_dwordx4 v[136:137], off
	v_lshl_add_u64 v[136:137], s[40:41], 0, v[134:135]
	s_mov_b32 m0, s72
	s_nop 0
	global_load_lds_dwordx4 v[136:137], off
	s_waitcnt vmcnt(6)
	s_barrier
	v_mfma_f32_16x16x32_bf16 v[52:55], v[188:191], v[156:159], v[52:55]
	v_mfma_f32_16x16x32_bf16 v[48:51], v[206:209], v[156:159], v[48:51]
	v_mfma_f32_16x16x32_bf16 v[36:39], v[188:191], v[164:167], v[36:39]
	v_mfma_f32_16x16x32_bf16 v[32:35], v[206:209], v[164:167], v[32:35]
	v_mfma_f32_16x16x32_bf16 v[20:23], v[188:191], v[172:175], v[20:23]
	v_mfma_f32_16x16x32_bf16 v[16:19], v[206:209], v[172:175], v[16:19]
	v_mfma_f32_16x16x32_bf16 v[4:7], v[188:191], v[180:183], v[4:7]
	v_mfma_f32_16x16x32_bf16 v[0:3], v[206:209], v[180:183], v[0:3]
	v_mfma_f32_16x16x32_bf16 v[52:55], v[198:201], v[160:163], v[52:55]
	v_mfma_f32_16x16x32_bf16 v[48:51], v[210:213], v[160:163], v[48:51]
	v_mfma_f32_16x16x32_bf16 v[36:39], v[198:201], v[168:171], v[36:39]
	v_mfma_f32_16x16x32_bf16 v[32:35], v[210:213], v[168:171], v[32:35]
	v_mfma_f32_16x16x32_bf16 v[20:23], v[198:201], v[176:179], v[20:23]
	v_mfma_f32_16x16x32_bf16 v[16:19], v[210:213], v[176:179], v[16:19]
	v_mfma_f32_16x16x32_bf16 v[4:7], v[198:201], v[184:187], v[4:7]
	v_mfma_f32_16x16x32_bf16 v[0:3], v[210:213], v[184:187], v[0:3]
	s_andn2_b64 vcc, exec, s[14:15]
	s_mov_b64 s[40:41], -1
	s_mov_b64 s[14:15], 0
	s_mov_b64 s[42:43], 0x100
	s_barrier
	s_cbranch_vccz .LBB0_1681
	v_mov_b32_e32 v137, v252
	s_lshl_b32 s0, s8, 8
	v_readfirstlane_b32 s1, v137
	s_ashr_i32 s7, s1, 2
	s_lshr_b32 s1, s1, 1
	s_andn2_b32 s7, s7, 63
	s_and_b32 s1, s1, 0x60
	v_lshrrev_b32_e32 v138, 1, v137
	s_lshl_b32 s6, s6, 8
	v_and_b32_e32 v147, 15, v137
	s_add_i32 s0, s7, s0
	v_and_b32_e32 v160, 24, v138
	s_or_b32 s31, s1, s6
	v_or_b32_e32 v136, s0, v147
	v_or_b32_e32 v156, s31, v160
	v_and_b32_e32 v153, 4, v138
	v_lshlrev_b32_e32 v137, 1, v137
	v_lshlrev_b32_e32 v138, 13, v156
	v_and_or_b32 v154, v137, 8, v153
	v_ashrrev_i32_e32 v137, 31, v136
	v_and_b32_e32 v152, 0x70000, v138
	v_lshl_add_u64 v[138:139], v[136:137], 2, s[24:25]
	global_load_dword v137, v[138:139], off
	v_or_b32_e32 v144, 16, v136
	v_ashrrev_i32_e32 v145, 31, v144
	v_or_b32_e32 v142, 32, v136
	v_lshl_add_u64 v[140:141], v[144:145], 2, s[24:25]
	v_ashrrev_i32_e32 v143, 31, v142
	global_load_dword v155, v[140:141], off
	v_lshl_add_u64 v[140:141], v[142:143], 2, s[24:25]
	global_load_dword v145, v[140:141], off
	v_or_b32_e32 v140, 48, v136
	v_ashrrev_i32_e32 v141, 31, v140
	v_lshl_add_u64 v[148:149], v[140:141], 2, s[24:25]
	global_load_dword v143, v[148:149], off
	v_add_u32_e32 v158, 0xffffc000, v136
	v_lshlrev_b32_e32 v146, 1, v158
	v_and_b32_e32 v141, 0x7fffffc3, v158
	v_and_b32_e32 v146, 8, v146
	v_or3_b32 v157, v141, v146, v153
	s_ashr_i32 s1, s0, 10
	s_and_b32 s35, s1, -8
	s_movk_i32 s1, 0x1fc3
	s_movk_i32 s44, 0x3fff
	v_and_or_b32 v159, v136, s1, v154
	s_movk_i32 s1, 0x1ff
	v_cmp_lt_i32_e64 s[12:13], s44, v136
	s_waitcnt vmcnt(0)
	v_fmamk_f32 v137, v137, 0x3b800000, v194
	v_cmp_gt_f32_e32 vcc, s2, v137
	v_mul_f32_e32 v141, 0x4b800000, v137
	s_nop 0
	v_cndmask_b32_e32 v137, v137, v141, vcc
	v_rsq_f32_e32 v137, v137
	s_nop 0
	v_mul_f32_e32 v141, 0x45800000, v137
	v_cndmask_b32_e32 v146, v137, v141, vcc
	v_pk_mul_f32 v[126:127], v[126:127], v[146:147] op_sel_hi:[1,0]
	v_pk_mul_f32 v[124:125], v[124:125], v[146:147] op_sel_hi:[1,0]
	v_cmp_lt_i32_e32 vcc, s1, v156
	v_add_u32_e32 v141, 0xfffffe00, v156
	s_and_saveexec_b64 s[6:7], vcc
	s_xor_b64 s[6:7], exec, s[6:7]
	s_cbranch_execz .LBB0_1688
	s_and_saveexec_b64 s[8:9], s[12:13]
	s_xor_b64 s[8:9], exec, s[8:9]
	v_lshlrev_b32_e32 v192, 6, v141
	v_lshl_add_u64 v[148:149], v[192:193], 1, s[22:23]
	s_or_saveexec_b64 s[8:9], s[8:9]
	v_mov_b32_e32 v137, 64
	v_mov_b32_e32 v161, v157
	s_xor_b64 exec, exec, s[8:9]
	v_lshrrev_b32_e32 v137, 6, v141
	v_add_u32_e32 v148, s35, v137
	v_ashrrev_i32_e32 v149, 31, v148
	v_lshlrev_b64 v[148:149], 20, v[148:149]
	v_lshl_add_u64 v[148:149], s[28:29], 0, v[148:149]
	v_lshlrev_b32_e32 v192, 1, v152
	v_lshl_add_u64 v[148:149], v[148:149], 0, v[192:193]
	v_mov_b32_e32 v137, 0x2000
	v_mov_b32_e32 v161, v159
	s_or_b64 exec, exec, s[8:9]
	v_lshlrev_b32_e32 v192, 1, v161
	v_lshl_add_u64 v[148:149], v[148:149], 0, v[192:193]
	v_cvt_pk_bf16_f32 v124, v124, s0
	v_lshlrev_b32_e32 v192, 1, v137
	global_store_short v[148:149], v124, off
	v_cvt_pk_bf16_f32 v161, v125, s0
	v_lshl_add_u64 v[124:125], v[148:149], 0, v[192:193]
	v_lshlrev_b32_e32 v192, 2, v137
	global_store_short v[124:125], v161, off
	v_cvt_pk_bf16_f32 v126, v126, s0
	v_lshl_add_u64 v[124:125], v[148:149], 0, v[192:193]
	global_store_short v[124:125], v126, off
	v_mul_u32_u24_e32 v124, 3, v137
	v_lshlrev_b32_e32 v192, 1, v124
	v_cvt_pk_bf16_f32 v126, v127, s0
	v_lshl_add_u64 v[124:125], v[148:149], 0, v[192:193]
	global_store_short v[124:125], v126, off

.LBB0_2698:
	s_add_u32 s23, s28, s36
	s_addc_u32 s33, s29, s37
	s_add_u32 s40, s23, 0x100
	s_addc_u32 s41, s33, 0
	s_and_b64 s[38:39], s[34:35], exec
	s_cselect_b32 s41, s0, s41
	s_cselect_b32 s40, s1, s40
	s_add_u32 s36, s26, s36
	s_addc_u32 s37, s27, s37
	s_add_u32 s36, s36, 0x100
	s_addc_u32 s37, s37, 0
	s_add_i32 s62, 0, 0x10000
	s_and_b64 s[34:35], s[34:35], exec
	s_cselect_b32 s43, s15, s37
	s_cselect_b32 s42, s17, s36
	s_add_u32 s44, s23, 0x40080
	s_addc_u32 s45, s33, 0
	s_add_i32 s66, s62, s51
	s_add_i32 m0, s25, 0xc000
	s_add_i32 s67, s25, 0xe000
	s_add_i32 s65, 0, 0x14000
	s_add_i32 s64, s66, 0x2000
	s_add_u32 s38, s42, 0x10000
	v_add_u32_e32 v60, s62, v208
	s_addc_u32 s39, s43, 0
	s_add_i32 s61, s65, s51
	ds_read_b128 v[40:43], v60
	ds_read_b128 v[44:47], v60 offset:1024
	ds_read_b128 v[56:59], v60 offset:2048
	ds_read_b128 v[60:63], v60 offset:3072
	s_add_i32 s60, s61, 0x2000
	s_add_i32 s59, 0, 0x18000
	s_add_u32 s36, s40, 0x40000
	s_addc_u32 s37, s41, 0
	s_add_i32 s58, s59, s51
	s_add_i32 s33, 0, 0x1c000
	s_add_i32 s23, s58, 0x2000
	s_add_u32 s34, s42, 0x10080
	s_addc_u32 s35, s43, 0
	s_add_i32 s63, s33, s51
	s_add_i32 s62, s63, 0x2000
	v_lshl_add_u64 v[182:183], s[44:45], 0, v[168:169]
	ds_read_b128 v[144:147], v209
	ds_read_b128 v[148:151], v209 offset:1024
	ds_read_b128 v[152:155], v209 offset:2048
	ds_read_b128 v[156:159], v209 offset:3072
	ds_read_b128 v[160:163], v209 offset:4096
	ds_read_b128 v[164:167], v209 offset:5120
	ds_read_b128 v[174:177], v209 offset:6144
	ds_read_b128 v[178:181], v209 offset:7168
	global_load_lds_dwordx4 v[182:183], off
	v_lshl_add_u64 v[182:183], s[44:45], 0, v[170:171]
	s_mov_b32 m0, s67
	s_nop 0
	global_load_lds_dwordx4 v[182:183], off
	s_waitcnt lgkmcnt(8)
	s_barrier
	s_waitcnt lgkmcnt(0)
	v_mfma_f32_16x16x32_bf16 v[140:143], v[40:43], v[144:147], v[140:143]
	v_mfma_f32_16x16x32_bf16 v[136:139], v[56:59], v[144:147], v[136:139]
	v_mfma_f32_16x16x32_bf16 v[124:127], v[40:43], v[152:155], v[124:127]
	v_mfma_f32_16x16x32_bf16 v[120:123], v[56:59], v[152:155], v[120:123]
	v_mfma_f32_16x16x32_bf16 v[108:111], v[40:43], v[160:163], v[108:111]
	v_mfma_f32_16x16x32_bf16 v[104:107], v[56:59], v[160:163], v[104:107]
	v_mfma_f32_16x16x32_bf16 v[92:95], v[40:43], v[174:177], v[92:95]
	v_mfma_f32_16x16x32_bf16 v[88:91], v[56:59], v[174:177], v[88:91]
	v_mfma_f32_16x16x32_bf16 v[140:143], v[44:47], v[148:151], v[140:143]
	v_mfma_f32_16x16x32_bf16 v[136:139], v[60:63], v[148:151], v[136:139]
	v_mfma_f32_16x16x32_bf16 v[124:127], v[44:47], v[156:159], v[124:127]
	v_mfma_f32_16x16x32_bf16 v[120:123], v[60:63], v[156:159], v[120:123]
	v_mfma_f32_16x16x32_bf16 v[108:111], v[44:47], v[164:167], v[108:111]
	v_mfma_f32_16x16x32_bf16 v[104:107], v[60:63], v[164:167], v[104:107]
	v_mfma_f32_16x16x32_bf16 v[92:95], v[44:47], v[178:181], v[92:95]
	v_mfma_f32_16x16x32_bf16 v[88:91], v[60:63], v[178:181], v[88:91]
	s_barrier
	v_add_u32_e32 v190, s65, v208
	s_mov_b32 m0, s66
	ds_read_b128 v[182:185], v190
	ds_read_b128 v[186:189], v190 offset:1024
	ds_read_b128 v[198:201], v190 offset:2048
	ds_read_b128 v[210:213], v190 offset:3072
	v_lshl_add_u64 v[190:191], s[42:43], 0, v[192:193]
	global_load_lds_dwordx4 v[190:191], off
	v_lshl_add_u64 v[206:207], s[42:43], 0, v[172:173]
	s_mov_b32 m0, s64
	s_nop 0
	global_load_lds_dwordx4 v[206:207], off
	s_barrier
	s_waitcnt lgkmcnt(0)
	v_mfma_f32_16x16x32_bf16 v[132:135], v[182:185], v[144:147], v[132:135]
	v_mfma_f32_16x16x32_bf16 v[128:131], v[198:201], v[144:147], v[128:131]
	v_mfma_f32_16x16x32_bf16 v[116:119], v[182:185], v[152:155], v[116:119]
	v_mfma_f32_16x16x32_bf16 v[112:115], v[198:201], v[152:155], v[112:115]
	v_mfma_f32_16x16x32_bf16 v[100:103], v[182:185], v[160:163], v[100:103]
	v_mfma_f32_16x16x32_bf16 v[96:99], v[198:201], v[160:163], v[96:99]
	v_mfma_f32_16x16x32_bf16 v[84:87], v[182:185], v[174:177], v[84:87]
	v_mfma_f32_16x16x32_bf16 v[80:83], v[198:201], v[174:177], v[80:83]
	v_mfma_f32_16x16x32_bf16 v[132:135], v[186:189], v[148:151], v[132:135]
	v_mfma_f32_16x16x32_bf16 v[128:131], v[210:213], v[148:151], v[128:131]
	v_mfma_f32_16x16x32_bf16 v[116:119], v[186:189], v[156:159], v[116:119]
	v_mfma_f32_16x16x32_bf16 v[112:115], v[210:213], v[156:159], v[112:115]
	v_mfma_f32_16x16x32_bf16 v[100:103], v[186:189], v[164:167], v[100:103]
	v_mfma_f32_16x16x32_bf16 v[96:99], v[210:213], v[164:167], v[96:99]
	v_mfma_f32_16x16x32_bf16 v[84:87], v[186:189], v[178:181], v[84:87]
	v_mfma_f32_16x16x32_bf16 v[80:83], v[210:213], v[178:181], v[80:83]
	s_mov_b32 m0, s25
	v_lshl_add_u64 v[214:215], s[40:41], 0, v[168:169]
	s_barrier
	ds_read_b128 v[144:147], v209 offset:16384
	ds_read_b128 v[148:151], v209 offset:17408
	ds_read_b128 v[152:155], v209 offset:18432
	ds_read_b128 v[156:159], v209 offset:19456
	ds_read_b128 v[160:163], v209 offset:20480
	ds_read_b128 v[164:167], v209 offset:21504
	ds_read_b128 v[174:177], v209 offset:22528
	ds_read_b128 v[178:181], v209 offset:23552
	global_load_lds_dwordx4 v[214:215], off
	v_lshl_add_u64 v[216:217], s[40:41], 0, v[170:171]
	s_mov_b32 m0, s52
	s_nop 0
	global_load_lds_dwordx4 v[216:217], off
	s_barrier
	s_waitcnt lgkmcnt(0)
	v_mfma_f32_16x16x32_bf16 v[76:79], v[40:43], v[144:147], v[76:79]
	v_mfma_f32_16x16x32_bf16 v[72:75], v[56:59], v[144:147], v[72:75]
	v_mfma_f32_16x16x32_bf16 v[52:55], v[40:43], v[152:155], v[52:55]
	v_mfma_f32_16x16x32_bf16 v[48:51], v[56:59], v[152:155], v[48:51]
	v_mfma_f32_16x16x32_bf16 v[28:31], v[40:43], v[160:163], v[28:31]
	v_mfma_f32_16x16x32_bf16 v[24:27], v[56:59], v[160:163], v[24:27]
	v_mfma_f32_16x16x32_bf16 v[12:15], v[40:43], v[174:177], v[12:15]
	v_mfma_f32_16x16x32_bf16 v[8:11], v[56:59], v[174:177], v[8:11]
	v_mfma_f32_16x16x32_bf16 v[76:79], v[44:47], v[148:151], v[76:79]
	v_mfma_f32_16x16x32_bf16 v[72:75], v[60:63], v[148:151], v[72:75]
	v_mfma_f32_16x16x32_bf16 v[52:55], v[44:47], v[156:159], v[52:55]
	v_mfma_f32_16x16x32_bf16 v[48:51], v[60:63], v[156:159], v[48:51]
	v_mfma_f32_16x16x32_bf16 v[28:31], v[44:47], v[164:167], v[28:31]
	v_mfma_f32_16x16x32_bf16 v[24:27], v[60:63], v[164:167], v[24:27]
	v_mfma_f32_16x16x32_bf16 v[12:15], v[44:47], v[178:181], v[12:15]
	v_mfma_f32_16x16x32_bf16 v[8:11], v[60:63], v[178:181], v[8:11]
	s_barrier
	s_mov_b32 m0, s61
	v_lshl_add_u64 v[40:41], s[38:39], 0, v[192:193]
	global_load_lds_dwordx4 v[40:41], off
	v_lshl_add_u64 v[40:41], s[38:39], 0, v[172:173]
	s_mov_b32 m0, s60
	s_nop 0
	global_load_lds_dwordx4 v[40:41], off
	s_waitcnt vmcnt(6)
	s_barrier
	v_mfma_f32_16x16x32_bf16 v[36:39], v[182:185], v[152:155], v[36:39]
	v_mfma_f32_16x16x32_bf16 v[32:35], v[198:201], v[152:155], v[32:35]
	v_mfma_f32_16x16x32_bf16 v[20:23], v[182:185], v[160:163], v[20:23]
	v_mfma_f32_16x16x32_bf16 v[16:19], v[198:201], v[160:163], v[16:19]
	v_mfma_f32_16x16x32_bf16 v[4:7], v[182:185], v[174:177], v[4:7]
	v_mfma_f32_16x16x32_bf16 v[0:3], v[198:201], v[174:177], v[0:3]
	v_mfma_f32_16x16x32_bf16 v[40:43], v[182:185], v[144:147], v[68:71]
	v_mfma_f32_16x16x32_bf16 v[44:47], v[198:201], v[144:147], v[64:67]
	v_mfma_f32_16x16x32_bf16 v[36:39], v[186:189], v[156:159], v[36:39]
	v_mfma_f32_16x16x32_bf16 v[32:35], v[210:213], v[156:159], v[32:35]
	v_mfma_f32_16x16x32_bf16 v[20:23], v[186:189], v[164:167], v[20:23]
	v_mfma_f32_16x16x32_bf16 v[16:19], v[210:213], v[164:167], v[16:19]
	v_mfma_f32_16x16x32_bf16 v[4:7], v[186:189], v[178:181], v[4:7]
	v_mfma_f32_16x16x32_bf16 v[0:3], v[210:213], v[178:181], v[0:3]
	v_mfma_f32_16x16x32_bf16 v[40:43], v[186:189], v[148:151], v[40:43]
	v_mfma_f32_16x16x32_bf16 v[44:47], v[210:213], v[148:151], v[44:47]
	v_add_u32_e32 v68, s59, v208
	s_barrier
	ds_read_b128 v[56:59], v68
	ds_read_b128 v[60:63], v68 offset:1024
	ds_read_b128 v[64:67], v68 offset:2048
	ds_read_b128 v[68:71], v68 offset:3072
	s_mov_b32 m0, s53
	v_lshl_add_u64 v[182:183], s[36:37], 0, v[168:169]
	ds_read_b128 v[144:147], v209 offset:32768
	ds_read_b128 v[148:151], v209 offset:33792
	ds_read_b128 v[152:155], v209 offset:34816
	ds_read_b128 v[156:159], v209 offset:35840
	ds_read_b128 v[160:163], v209 offset:36864
	ds_read_b128 v[164:167], v209 offset:37888
	ds_read_b128 v[174:177], v209 offset:38912
	ds_read_b128 v[178:181], v209 offset:39936
	global_load_lds_dwordx4 v[182:183], off
	v_lshl_add_u64 v[182:183], s[36:37], 0, v[170:171]
	s_mov_b32 m0, s54
	s_nop 0
	global_load_lds_dwordx4 v[182:183], off
	s_waitcnt lgkmcnt(8)
	s_barrier
	s_waitcnt lgkmcnt(0)
	v_mfma_f32_16x16x32_bf16 v[140:143], v[56:59], v[144:147], v[140:143]
	v_mfma_f32_16x16x32_bf16 v[136:139], v[64:67], v[144:147], v[136:139]
	v_mfma_f32_16x16x32_bf16 v[124:127], v[56:59], v[152:155], v[124:127]
	v_mfma_f32_16x16x32_bf16 v[120:123], v[64:67], v[152:155], v[120:123]
	v_mfma_f32_16x16x32_bf16 v[108:111], v[56:59], v[160:163], v[108:111]
	v_mfma_f32_16x16x32_bf16 v[104:107], v[64:67], v[160:163], v[104:107]
	v_mfma_f32_16x16x32_bf16 v[92:95], v[56:59], v[174:177], v[92:95]
	v_mfma_f32_16x16x32_bf16 v[88:91], v[64:67], v[174:177], v[88:91]
	v_mfma_f32_16x16x32_bf16 v[140:143], v[60:63], v[148:151], v[140:143]
	v_mfma_f32_16x16x32_bf16 v[136:139], v[68:71], v[148:151], v[136:139]
	v_mfma_f32_16x16x32_bf16 v[124:127], v[60:63], v[156:159], v[124:127]
	v_mfma_f32_16x16x32_bf16 v[120:123], v[68:71], v[156:159], v[120:123]
	v_mfma_f32_16x16x32_bf16 v[108:111], v[60:63], v[164:167], v[108:111]
	v_mfma_f32_16x16x32_bf16 v[104:107], v[68:71], v[164:167], v[104:107]
	v_mfma_f32_16x16x32_bf16 v[92:95], v[60:63], v[178:181], v[92:95]
	v_mfma_f32_16x16x32_bf16 v[88:91], v[68:71], v[178:181], v[88:91]
	s_barrier
	s_mov_b32 m0, s58
	v_add_u32_e32 v196, s33, v208
	v_lshl_add_u64 v[190:191], v[190:191], 0, s[80:81]
	ds_read_b128 v[182:185], v196
	ds_read_b128 v[186:189], v196 offset:1024
	ds_read_b128 v[198:201], v196 offset:2048
	ds_read_b128 v[210:213], v196 offset:3072
	global_load_lds_dwordx4 v[190:191], off
	v_lshl_add_u64 v[190:191], v[206:207], 0, s[80:81]
	s_mov_b32 m0, s23
	s_nop 0
	global_load_lds_dwordx4 v[190:191], off
	s_barrier
	s_waitcnt lgkmcnt(0)
	v_mfma_f32_16x16x32_bf16 v[132:135], v[182:185], v[144:147], v[132:135]
	v_mfma_f32_16x16x32_bf16 v[128:131], v[198:201], v[144:147], v[128:131]
	v_mfma_f32_16x16x32_bf16 v[116:119], v[182:185], v[152:155], v[116:119]
	v_mfma_f32_16x16x32_bf16 v[112:115], v[198:201], v[152:155], v[112:115]
	v_mfma_f32_16x16x32_bf16 v[100:103], v[182:185], v[160:163], v[100:103]
	v_mfma_f32_16x16x32_bf16 v[96:99], v[198:201], v[160:163], v[96:99]
	v_mfma_f32_16x16x32_bf16 v[84:87], v[182:185], v[174:177], v[84:87]
	v_mfma_f32_16x16x32_bf16 v[80:83], v[198:201], v[174:177], v[80:83]
	v_mfma_f32_16x16x32_bf16 v[132:135], v[186:189], v[148:151], v[132:135]
	v_mfma_f32_16x16x32_bf16 v[128:131], v[210:213], v[148:151], v[128:131]
	v_mfma_f32_16x16x32_bf16 v[116:119], v[186:189], v[156:159], v[116:119]
	v_mfma_f32_16x16x32_bf16 v[112:115], v[210:213], v[156:159], v[112:115]
	v_mfma_f32_16x16x32_bf16 v[100:103], v[186:189], v[164:167], v[100:103]
	v_mfma_f32_16x16x32_bf16 v[96:99], v[210:213], v[164:167], v[96:99]
	v_mfma_f32_16x16x32_bf16 v[84:87], v[186:189], v[178:181], v[84:87]
	v_mfma_f32_16x16x32_bf16 v[80:83], v[210:213], v[178:181], v[80:83]
	s_mov_b32 m0, s55
	v_lshl_add_u64 v[190:191], v[214:215], 0, s[80:81]
	s_barrier
	ds_read_b128 v[144:147], v209 offset:49152
	ds_read_b128 v[148:151], v209 offset:50176
	ds_read_b128 v[152:155], v209 offset:51200
	ds_read_b128 v[156:159], v209 offset:52224
	ds_read_b128 v[160:163], v209 offset:53248
	ds_read_b128 v[164:167], v209 offset:54272
	ds_read_b128 v[174:177], v209 offset:55296
	ds_read_b128 v[178:181], v209 offset:56320
	global_load_lds_dwordx4 v[190:191], off
	v_lshl_add_u64 v[190:191], v[216:217], 0, s[80:81]
	s_mov_b32 m0, s56
	s_nop 0
	global_load_lds_dwordx4 v[190:191], off
	s_barrier
	s_waitcnt lgkmcnt(0)
	v_mfma_f32_16x16x32_bf16 v[76:79], v[56:59], v[144:147], v[76:79]
	v_mfma_f32_16x16x32_bf16 v[72:75], v[64:67], v[144:147], v[72:75]
	v_mfma_f32_16x16x32_bf16 v[52:55], v[56:59], v[152:155], v[52:55]
	v_mfma_f32_16x16x32_bf16 v[48:51], v[64:67], v[152:155], v[48:51]
	v_mfma_f32_16x16x32_bf16 v[28:31], v[56:59], v[160:163], v[28:31]
	v_mfma_f32_16x16x32_bf16 v[24:27], v[64:67], v[160:163], v[24:27]
	v_mfma_f32_16x16x32_bf16 v[12:15], v[56:59], v[174:177], v[12:15]
	v_mfma_f32_16x16x32_bf16 v[8:11], v[64:67], v[174:177], v[8:11]
	v_mfma_f32_16x16x32_bf16 v[76:79], v[60:63], v[148:151], v[76:79]
	v_mfma_f32_16x16x32_bf16 v[72:75], v[68:71], v[148:151], v[72:75]
	v_mfma_f32_16x16x32_bf16 v[52:55], v[60:63], v[156:159], v[52:55]
	v_mfma_f32_16x16x32_bf16 v[48:51], v[68:71], v[156:159], v[48:51]
	v_mfma_f32_16x16x32_bf16 v[28:31], v[60:63], v[164:167], v[28:31]
	v_mfma_f32_16x16x32_bf16 v[24:27], v[68:71], v[164:167], v[24:27]
	v_mfma_f32_16x16x32_bf16 v[12:15], v[60:63], v[178:181], v[12:15]
	v_mfma_f32_16x16x32_bf16 v[8:11], v[68:71], v[178:181], v[8:11]
	s_barrier
	s_mov_b32 m0, s63
	v_lshl_add_u64 v[56:57], s[34:35], 0, v[192:193]
	global_load_lds_dwordx4 v[56:57], off
	v_lshl_add_u64 v[56:57], s[34:35], 0, v[172:173]
	s_mov_b32 m0, s62
	s_nop 0
	global_load_lds_dwordx4 v[56:57], off
	s_waitcnt vmcnt(6)
	s_barrier
	v_mfma_f32_16x16x32_bf16 v[40:43], v[182:185], v[144:147], v[40:43]
	v_mfma_f32_16x16x32_bf16 v[68:71], v[186:189], v[148:151], v[40:43]
	v_mfma_f32_16x16x32_bf16 v[40:43], v[198:201], v[144:147], v[44:47]
	v_mfma_f32_16x16x32_bf16 v[36:39], v[182:185], v[152:155], v[36:39]
	v_mfma_f32_16x16x32_bf16 v[32:35], v[198:201], v[152:155], v[32:35]
	v_mfma_f32_16x16x32_bf16 v[20:23], v[182:185], v[160:163], v[20:23]
	v_mfma_f32_16x16x32_bf16 v[16:19], v[198:201], v[160:163], v[16:19]
	v_mfma_f32_16x16x32_bf16 v[4:7], v[182:185], v[174:177], v[4:7]
	v_mfma_f32_16x16x32_bf16 v[0:3], v[198:201], v[174:177], v[0:3]
	v_mfma_f32_16x16x32_bf16 v[64:67], v[210:213], v[148:151], v[40:43]
	v_mfma_f32_16x16x32_bf16 v[36:39], v[186:189], v[156:159], v[36:39]
	v_mfma_f32_16x16x32_bf16 v[32:35], v[210:213], v[156:159], v[32:35]
	v_mfma_f32_16x16x32_bf16 v[20:23], v[186:189], v[164:167], v[20:23]
	v_mfma_f32_16x16x32_bf16 v[16:19], v[210:213], v[164:167], v[16:19]
	v_mfma_f32_16x16x32_bf16 v[4:7], v[186:189], v[178:181], v[4:7]
	v_mfma_f32_16x16x32_bf16 v[0:3], v[210:213], v[178:181], v[0:3]
	s_andn2_b64 vcc, exec, s[30:31]
	s_mov_b64 s[34:35], -1
	s_mov_b64 s[30:31], 0
	s_mov_b64 s[36:37], 0x100
	s_barrier
	s_cbranch_vccz .LBB0_2698
	v_mov_b32_e32 v144, v252
	s_lshl_b32 s1, s24, 8
	v_readfirstlane_b32 s0, v144
	s_ashr_i32 s15, s0, 2
	s_andn2_b32 s15, s15, 63
	s_add_i32 s15, s15, s1
	v_and_b32_e32 v145, 64, v195
	v_lshrrev_b32_e32 v40, 1, v144
	v_and_or_b32 v178, v144, 15, s15
	v_xor_b32_e32 v144, 16, v195
	v_add_u32_e32 v145, 64, v145
	v_cmp_lt_i32_e32 vcc, v144, v145
	s_lshr_b32 s0, s0, 1
	s_lshl_b32 s1, s22, 8
	v_cndmask_b32_e32 v144, v195, v144, vcc
	s_and_b32 s0, s0, 0x60
	v_lshlrev_b32_e32 v198, 2, v144
	v_xor_b32_e32 v144, 32, v195
	s_or_b32 s0, s0, s1
	v_cmp_lt_i32_e32 vcc, v144, v145
	v_and_or_b32 v176, v40, 24, s0
	v_ashrrev_i32_e32 v179, 31, v178
	v_cndmask_b32_e32 v144, v195, v144, vcc
	v_ashrrev_i32_e32 v177, 31, v176
	v_lshlrev_b32_e32 v196, 2, v144
	v_lshlrev_b64 v[144:145], 10, v[178:179]
	v_lshl_add_u64 v[146:147], v[144:145], 0, v[176:177]
	v_lshlrev_b64 v[146:147], 1, v[146:147]
	v_lshl_add_u64 v[44:45], v[176:177], 2, s[10:11]
	v_lshl_add_u64 v[188:189], s[6:7], 0, v[146:147]
	v_lshl_add_u64 v[206:207], s[8:9], 0, v[146:147]
	global_load_dwordx4 v[56:59], v[44:45], off offset:16
	global_load_dwordx4 v[60:63], v[44:45], off
	global_load_dwordx4 v[40:43], v[44:45], off offset:528
	s_nop 0
	global_load_dwordx4 v[44:47], v[44:45], off offset:512
	v_or_b32_e32 v174, 0x80, v176
	global_load_dwordx4 v[210:213], v[188:189], off
	global_load_dwordx4 v[164:167], v[188:189], off offset:256
	global_load_dwordx4 v[214:217], v[206:207], off
	v_ashrrev_i32_e32 v175, 31, v174
	v_or_b32_e32 v184, 16, v178
	v_lshl_add_u64 v[144:145], v[144:145], 0, v[174:175]
	v_ashrrev_i32_e32 v185, 31, v184
	v_lshl_add_u64 v[190:191], v[144:145], 1, s[8:9]
	v_lshlrev_b64 v[144:145], 10, v[184:185]
	v_lshl_add_u64 v[146:147], v[144:145], 0, v[176:177]
	v_lshlrev_b64 v[146:147], 1, v[146:147]
	v_lshl_add_u64 v[148:149], v[144:145], 0, v[174:175]
	v_lshl_add_u64 v[180:181], s[6:7], 0, v[146:147]
	v_lshl_add_u64 v[186:187], s[8:9], 0, v[146:147]
	v_lshl_add_u64 v[182:183], v[148:149], 1, s[8:9]
	global_load_dwordx4 v[160:163], v[190:191], off
	global_load_dwordx4 v[156:159], v[180:181], off
	global_load_dwordx4 v[144:147], v[180:181], off offset:256
	global_load_dwordx4 v[152:155], v[186:187], off
	global_load_dwordx4 v[148:151], v[182:183], off
	v_cmp_gt_u32_e32 vcc, 16, v195
	s_waitcnt vmcnt(0)
	v_lshlrev_b32_e32 v200, 16, v210
	v_and_b32_e32 v201, 0xffff0000, v210
	v_lshlrev_b32_e32 v218, 16, v214
	v_and_b32_e32 v219, 0xffff0000, v214
	v_lshlrev_b32_e32 v210, 16, v211
	v_and_b32_e32 v211, 0xffff0000, v211
	v_lshlrev_b32_e32 v214, 16, v215
	v_and_b32_e32 v215, 0xffff0000, v215
	v_pk_add_f32 v[200:201], v[200:201], v[218:219]
	v_pk_add_f32 v[210:211], v[210:211], v[214:215]
	v_pk_fma_f32 v[200:201], v[140:141], v[60:61], v[200:201]
	v_pk_fma_f32 v[210:211], v[142:143], v[62:63], v[210:211]
	v_lshlrev_b32_e32 v140, 16, v212
	v_and_b32_e32 v141, 0xffff0000, v212
	v_lshlrev_b32_e32 v142, 16, v216
	v_and_b32_e32 v143, 0xffff0000, v216
	v_pk_add_f32 v[140:141], v[140:141], v[142:143]
	v_lshlrev_b32_e32 v142, 16, v213
	v_and_b32_e32 v143, 0xffff0000, v213
	v_lshlrev_b32_e32 v212, 16, v217
	v_and_b32_e32 v213, 0xffff0000, v217
	v_pk_add_f32 v[142:143], v[142:143], v[212:213]
	v_pk_fma_f32 v[214:215], v[136:137], v[56:57], v[140:141]
	v_cvt_pk_bf16_f32 v136, v200, v201
	v_pk_fma_f32 v[212:213], v[138:139], v[58:59], v[142:143]
	v_and_b32_e32 v139, 0xffff0000, v136
	v_lshlrev_b32_e32 v138, 16, v136
	v_pk_add_f32 v[138:139], v[200:201], v[138:139] neg_lo:[0,1] neg_hi:[0,1]
	v_cvt_pk_bf16_f32 v137, v210, v211
	v_cvt_pk_bf16_f32 v140, v138, v139
	v_and_b32_e32 v139, 0xffff0000, v137
	v_lshlrev_b32_e32 v138, 16, v137
	v_pk_add_f32 v[138:139], v[210:211], v[138:139] neg_lo:[0,1] neg_hi:[0,1]
	s_nop 0
	v_cvt_pk_bf16_f32 v141, v138, v139
	v_cvt_pk_bf16_f32 v138, v214, v215
	v_cvt_pk_bf16_f32 v139, v212, v213
	v_and_b32_e32 v143, 0xffff0000, v138
	v_lshlrev_b32_e32 v142, 16, v138
	v_and_b32_e32 v217, 0xffff0000, v139
	v_lshlrev_b32_e32 v216, 16, v139
	v_pk_add_f32 v[142:143], v[214:215], v[142:143] neg_lo:[0,1] neg_hi:[0,1]
	v_pk_add_f32 v[216:217], v[212:213], v[216:217] neg_lo:[0,1] neg_hi:[0,1]
	v_cvt_pk_bf16_f32 v142, v142, v143
	v_cvt_pk_bf16_f32 v143, v216, v217
	global_store_dwordx4 v[188:189], v[136:139], off
	global_store_dwordx4 v[206:207], v[140:143], off
	s_nop 0
	v_pk_mul_f32 v[138:139], v[214:215], v[214:215]
	v_pk_mul_f32 v[136:137], v[212:213], v[212:213]
	v_pk_fma_f32 v[138:139], v[200:201], v[200:201], v[138:139]
	v_pk_fma_f32 v[136:137], v[210:211], v[210:211], v[136:137]
	v_add_f32_e32 v138, v138, v139
	v_add_f32_e32 v136, v136, v138
	v_add_f32_e32 v136, v137, v136
	ds_bpermute_b32 v137, v198, v136
	s_waitcnt lgkmcnt(0)
	v_add_f32_e32 v138, v136, v137
	ds_bpermute_b32 v139, v196, v138
	v_lshl_add_u64 v[136:137], v[178:179], 2, s[12:13]
	s_and_saveexec_b64 s[22:23], vcc
	s_cbranch_execz .LBB0_2701
	s_waitcnt lgkmcnt(0)
	v_add_f32_e32 v138, v138, v139
	global_atomic_add_f32 v[136:137], v138, off
